# v20 + MINI phase compute rewritten: the four row reductions (6-step lane butterflies) run interleaved (one LDS round trip per step for all four) instead of back to back
# speedup vs baseline: 1.0044x; 1.0011x over previous
; __device__ __forceinline__ unsigned cvt_pk_bf16(float lo, float hi) { unsigned r; asm volatile("v_cvt_pk_bf16_f32 %0, %1, %2" : "=v"(r) : "v"(lo), "v"(hi)); return r; }
; __device__ __forceinline__ float bf_lo(unsigned w) { return __uint_as_float(w << 16); }
; __device__ __forceinline__ float bf_hi(unsigned w) { return __uint_as_float(w & 0xffff0000u); }
; __device__ __forceinline__ float wave_sum(float v) {
; #pragma unroll
;     for (int o = 1; o < 64; o <<= 1) v += __shfl_xor(v, o);
;     return v;
; __global__ void __launch_bounds__(512, 2) mega(Args a) {
;     ...
;                     for (int rr = 0; rr < 2; ++rr) { const int m = m0 + rr; bf16_t* P = PROJ + (size_t)m * INP;
;                         { const u32x4 w = wq[rr];
;                           float ss = bf_lo(w.x) * bf_lo(w.x) + bf_hi(w.x) * bf_hi(w.x) + bf_lo(w.y) * bf_lo(w.y) + bf_hi(w.y) * bf_hi(w.y) + bf_lo(w.z) * bf_lo(w.z) + bf_hi(w.z) * bf_hi(w.z) + bf_lo(w.w) * bf_lo(w.w) + bf_hi(w.w) * bf_hi(w.w);
;                           const float rstd = __builtin_amdgcn_rsqf(wave_sum(ss) * (1.f / 384.f) + NORM_EPS);
;                           if (lane < 48) { const f32x4 g0 = *(const f32x4*)(gq + lane * 8), g1 = *(const f32x4*)(gq + lane * 8 + 4); u32x4 o;
;                               o.x = cvt_pk_bf16(bf_lo(w.x) * rstd * g0.x, bf_hi(w.x) * rstd * g0.y); o.y = cvt_pk_bf16(bf_lo(w.y) * rstd * g0.z, bf_hi(w.y) * rstd * g0.w);
;                               o.z = cvt_pk_bf16(bf_lo(w.z) * rstd * g1.x, bf_hi(w.z) * rstd * g1.y); o.w = cvt_pk_bf16(bf_lo(w.w) * rstd * g1.z, bf_hi(w.w) * rstd * g1.w);
;                               *(u32x4*)(P + C_CQ + lane * 8) = o; } }
;                         { const u32x4 w = wk[rr];
;                           float ss = bf_lo(w.x) * bf_lo(w.x) + bf_hi(w.x) * bf_hi(w.x) + bf_lo(w.y) * bf_lo(w.y) + bf_hi(w.y) * bf_hi(w.y) + bf_lo(w.z) * bf_lo(w.z) + bf_hi(w.z) * bf_hi(w.z) + bf_lo(w.w) * bf_lo(w.w) + bf_hi(w.w) * bf_hi(w.w);
;                           const float rstd = __builtin_amdgcn_rsqf(wave_sum(ss) * (1.f / 256.f) + NORM_EPS);
.LBB0_1539:
	s_or_b64 exec, exec, s[10:11]
	v_and_b32_e32 v125, 0xffff0000, v8
	v_lshlrev_b32_e32 v124, 16, v8
	v_mul_f32_e32 v132, v125, v125
	v_fmac_f32_e32 v132, v124, v124
	v_lshlrev_b32_e32 v126, 16, v9
	v_fmac_f32_e32 v132, v126, v126
	v_and_b32_e32 v127, 0xffff0000, v9
	v_fmac_f32_e32 v132, v127, v127
	v_lshlrev_b32_e32 v128, 16, v10
	v_fmac_f32_e32 v132, v128, v128
	v_and_b32_e32 v129, 0xffff0000, v10
	v_fmac_f32_e32 v132, v129, v129
	v_lshlrev_b32_e32 v130, 16, v11
	v_fmac_f32_e32 v132, v130, v130
	v_and_b32_e32 v131, 0xffff0000, v11
	v_fmac_f32_e32 v132, v131, v131
	v_and_b32_e32 v137, 0xffff0000, v16
	v_lshlrev_b32_e32 v136, 16, v16
	v_mul_f32_e32 v144, v137, v137
	v_fmac_f32_e32 v144, v136, v136
	v_lshlrev_b32_e32 v138, 16, v17
	v_fmac_f32_e32 v144, v138, v138
	v_and_b32_e32 v139, 0xffff0000, v17
	v_fmac_f32_e32 v144, v139, v139
	v_lshlrev_b32_e32 v140, 16, v18
	v_fmac_f32_e32 v144, v140, v140
	v_and_b32_e32 v141, 0xffff0000, v18
	v_fmac_f32_e32 v144, v141, v141
	v_lshlrev_b32_e32 v142, 16, v19
	v_fmac_f32_e32 v144, v142, v142
	v_and_b32_e32 v143, 0xffff0000, v19
	v_fmac_f32_e32 v144, v143, v143
	v_and_b32_e32 v149, 0xffff0000, v12
	v_lshlrev_b32_e32 v148, 16, v12
	v_mul_f32_e32 v156, v149, v149
	v_fmac_f32_e32 v156, v148, v148
	v_lshlrev_b32_e32 v150, 16, v13
	v_fmac_f32_e32 v156, v150, v150
	v_and_b32_e32 v151, 0xffff0000, v13
	v_fmac_f32_e32 v156, v151, v151
	v_lshlrev_b32_e32 v152, 16, v14
	v_fmac_f32_e32 v156, v152, v152
	v_and_b32_e32 v153, 0xffff0000, v14
	v_fmac_f32_e32 v156, v153, v153
	v_lshlrev_b32_e32 v154, 16, v15
	v_fmac_f32_e32 v156, v154, v154
	v_and_b32_e32 v155, 0xffff0000, v15
	v_fmac_f32_e32 v156, v155, v155
	v_and_b32_e32 v161, 0xffff0000, v0
	v_lshlrev_b32_e32 v160, 16, v0
	v_mul_f32_e32 v168, v161, v161
	v_fmac_f32_e32 v168, v160, v160
	v_lshlrev_b32_e32 v162, 16, v1
	v_fmac_f32_e32 v168, v162, v162
	v_and_b32_e32 v163, 0xffff0000, v1
	v_fmac_f32_e32 v168, v163, v163
	v_lshlrev_b32_e32 v164, 16, v2
	v_fmac_f32_e32 v168, v164, v164
	v_and_b32_e32 v165, 0xffff0000, v2
	v_fmac_f32_e32 v168, v165, v165
	v_lshlrev_b32_e32 v166, 16, v3
	v_fmac_f32_e32 v168, v166, v166
	v_and_b32_e32 v167, 0xffff0000, v3
	v_fmac_f32_e32 v168, v167, v167
	ds_bpermute_b32 v133, v39, v132
	ds_bpermute_b32 v145, v39, v144
	ds_bpermute_b32 v157, v39, v156
	ds_bpermute_b32 v169, v39, v168
	s_waitcnt lgkmcnt(0)
	v_add_f32_e32 v132, v132, v133
	v_add_f32_e32 v144, v144, v145
	v_add_f32_e32 v156, v156, v157
	v_add_f32_e32 v168, v168, v169
	ds_bpermute_b32 v133, v40, v132
	ds_bpermute_b32 v145, v40, v144
	ds_bpermute_b32 v157, v40, v156
	ds_bpermute_b32 v169, v40, v168
	s_waitcnt lgkmcnt(0)
	v_add_f32_e32 v132, v132, v133
	v_add_f32_e32 v144, v144, v145
	v_add_f32_e32 v156, v156, v157
	v_add_f32_e32 v168, v168, v169
	ds_bpermute_b32 v133, v41, v132
	ds_bpermute_b32 v145, v41, v144
	ds_bpermute_b32 v157, v41, v156
	ds_bpermute_b32 v169, v41, v168
	s_waitcnt lgkmcnt(0)
	v_add_f32_e32 v132, v132, v133
	v_add_f32_e32 v144, v144, v145
	v_add_f32_e32 v156, v156, v157
	v_add_f32_e32 v168, v168, v169
	ds_bpermute_b32 v133, v42, v132
	ds_bpermute_b32 v145, v42, v144
	ds_bpermute_b32 v157, v42, v156
	ds_bpermute_b32 v169, v42, v168
	s_waitcnt lgkmcnt(0)
	v_add_f32_e32 v132, v132, v133
	v_add_f32_e32 v144, v144, v145
	v_add_f32_e32 v156, v156, v157
	v_add_f32_e32 v168, v168, v169
	ds_bpermute_b32 v133, v43, v132
	ds_bpermute_b32 v145, v43, v144
	ds_bpermute_b32 v157, v43, v156
	ds_bpermute_b32 v169, v43, v168
	s_waitcnt lgkmcnt(0)
	v_add_f32_e32 v132, v132, v133
	v_add_f32_e32 v144, v144, v145
	v_add_f32_e32 v156, v156, v157
	v_add_f32_e32 v168, v168, v169
	ds_bpermute_b32 v133, v44, v132
	ds_bpermute_b32 v145, v44, v144
	ds_bpermute_b32 v157, v44, v156
	ds_bpermute_b32 v169, v44, v168
	s_waitcnt lgkmcnt(0)
; __device__ __forceinline__ unsigned cvt_pk_bf16(float lo, float hi) { unsigned r; asm volatile("v_cvt_pk_bf16_f32 %0, %1, %2" : "=v"(r) : "v"(lo), "v"(hi)); return r; }
; __device__ __forceinline__ float bf_lo(unsigned w) { return __uint_as_float(w << 16); }
; __device__ __forceinline__ float bf_hi(unsigned w) { return __uint_as_float(w & 0xffff0000u); }
; __global__ void __launch_bounds__(512, 2) mega(Args a) {
;     ...
;                           const float rstd = __builtin_amdgcn_rsqf(wave_sum(ss) * (1.f / 384.f) + NORM_EPS);
;                           if (lane < 48) { const f32x4 g0 = *(const f32x4*)(gq + lane * 8), g1 = *(const f32x4*)(gq + lane * 8 + 4); u32x4 o;
;                               o.x = cvt_pk_bf16(bf_lo(w.x) * rstd * g0.x, bf_hi(w.x) * rstd * g0.y); o.y = cvt_pk_bf16(bf_lo(w.y) * rstd * g0.z, bf_hi(w.y) * rstd * g0.w);
;                               o.z = cvt_pk_bf16(bf_lo(w.z) * rstd * g1.x, bf_hi(w.z) * rstd * g1.y); o.w = cvt_pk_bf16(bf_lo(w.w) * rstd * g1.z, bf_hi(w.w) * rstd * g1.w);
;                               *(u32x4*)(P + C_CQ + lane * 8) = o; } }
;                         { const u32x4 w = wk[rr];
;                           float ss = bf_lo(w.x) * bf_lo(w.x) + bf_hi(w.x) * bf_hi(w.x) + bf_lo(w.y) * bf_lo(w.y) + bf_hi(w.y) * bf_hi(w.y) + bf_lo(w.z) * bf_lo(w.z) + bf_hi(w.z) * bf_hi(w.z) + bf_lo(w.w) * bf_lo(w.w) + bf_hi(w.w) * bf_hi(w.w);
;                           const float rstd = __builtin_amdgcn_rsqf(wave_sum(ss) * (1.f / 256.f) + NORM_EPS);
;                           if (lane < 32) { const f32x4 g0 = *(const f32x4*)(gkv + lane * 8), g1 = *(const f32x4*)(gkv + lane * 8 + 4); u32x4 o;
;                               o.x = cvt_pk_bf16(bf_lo(w.x) * rstd * g0.x, bf_hi(w.x) * rstd * g0.y); o.y = cvt_pk_bf16(bf_lo(w.y) * rstd * g0.z, bf_hi(w.y) * rstd * g0.w);
;                               o.z = cvt_pk_bf16(bf_lo(w.z) * rstd * g1.x, bf_hi(w.z) * rstd * g1.y); o.w = cvt_pk_bf16(bf_lo(w.w) * rstd * g1.z, bf_hi(w.w) * rstd * g1.w);
;                               *(u32x4*)(P + C_CKV + lane * 8) = o; } }
;                         if (lane < 16) { const unsigned w = cvt_pk_bf16(x1[rr] * cs[rr].x - x2[rr] * cs[rr].y, x1[rr] * cs[rr].y + x2[rr] * cs[rr].x);
;                             P[C_KPE + lane] = (bf16_t)(w & 0xffff); P[C_KPE + 16 + lane] = (bf16_t)(w >> 16); }
	v_add_f32_e32 v132, v132, v133
	v_add_f32_e32 v144, v144, v145
	v_add_f32_e32 v156, v156, v157
	v_add_f32_e32 v168, v168, v169
	s_and_saveexec_b64 s[10:11], s[40:41]
	v_fmamk_f32 v132, v132, 0x3b2aaaab, v192
	v_rsq_f32_e32 v132, v132
	v_add_co_u32_e32 v134, vcc, 0x5003000, v28
	s_nop 1
	v_addc_co_u32_e32 v135, vcc, 0, v29, vcc
	v_mul_f32_e32 v124, v132, v124
	v_mul_f32_e32 v126, v132, v126
	v_mul_f32_e32 v128, v132, v128
	v_mul_f32_e32 v130, v132, v130
	v_mul_f32_e32 v125, v132, v125
	v_mul_f32_e32 v127, v132, v127
	v_mul_f32_e32 v129, v132, v129
	v_mul_f32_e32 v131, v132, v131
	v_mul_f32_e32 v124, v124, v64
	v_mul_f32_e32 v125, v125, v65
	v_mul_f32_e32 v126, v126, v66
	v_mul_f32_e32 v127, v127, v67
	v_mul_f32_e32 v128, v128, v68
	v_mul_f32_e32 v129, v129, v69
	v_mul_f32_e32 v130, v130, v70
	v_mul_f32_e32 v131, v131, v71
	v_cvt_pk_bf16_f32 v8, v124, v125
	v_cvt_pk_bf16_f32 v9, v126, v127
	v_cvt_pk_bf16_f32 v10, v128, v129
	v_cvt_pk_bf16_f32 v11, v130, v131
	s_nop 0
	global_store_dwordx4 v[134:135], v[8:11], off
	s_mov_b64 exec, s[10:11]
	s_and_saveexec_b64 s[10:11], s[42:43]
	v_fmamk_f32 v144, v144, 0x3b800000, v192
	v_rsq_f32_e32 v144, v144
	v_add_co_u32_e32 v146, vcc, 0x5003000, v28
	s_nop 1
	v_addc_co_u32_e32 v147, vcc, 0, v29, vcc
	v_mul_f32_e32 v136, v144, v136
	v_mul_f32_e32 v138, v144, v138
	v_mul_f32_e32 v140, v144, v140
	v_mul_f32_e32 v142, v144, v142
	v_mul_f32_e32 v137, v144, v137
	v_mul_f32_e32 v139, v144, v139
	v_mul_f32_e32 v141, v144, v141
	v_mul_f32_e32 v143, v144, v143
	v_mul_f32_e32 v136, v136, v72
	v_mul_f32_e32 v137, v137, v73
	v_mul_f32_e32 v138, v138, v74
	v_mul_f32_e32 v139, v139, v75
	v_mul_f32_e32 v140, v140, v76
	v_mul_f32_e32 v141, v141, v77
	v_mul_f32_e32 v142, v142, v78
	v_mul_f32_e32 v143, v143, v79
	v_cvt_pk_bf16_f32 v16, v136, v137
	v_cvt_pk_bf16_f32 v17, v138, v139
	v_cvt_pk_bf16_f32 v18, v140, v141
	v_cvt_pk_bf16_f32 v19, v142, v143
	s_nop 0
	global_store_dwordx4 v[146:147], v[16:19], off offset:768
	s_mov_b64 exec, s[10:11]
	s_and_saveexec_b64 s[10:11], s[44:45]
	v_mul_f32_e32 v172, v32, v37
	v_fma_f32 v172, v38, v36, -v172
	v_mul_f32_e32 v173, v38, v37
	v_add_co_u32_e32 v174, vcc, 0x5003000, v30
	v_fmac_f32_e32 v173, v32, v36
	v_cvt_pk_bf16_f32 v172, v172, v173
	s_nop 0
	v_addc_co_u32_e32 v175, vcc, 0, v31, vcc
	global_store_short v[174:175], v172, off offset:1280
	global_store_short_d16_hi v[174:175], v172, off offset:1312
	s_mov_b64 exec, s[10:11]
	s_and_saveexec_b64 s[10:11], s[40:41]
	v_fmamk_f32 v156, v156, 0x3b2aaaab, v192
	v_rsq_f32_e32 v156, v156
	v_add_co_u32_e32 v158, vcc, 0x5006000, v28
	s_nop 1
	v_addc_co_u32_e32 v159, vcc, 0, v29, vcc
	v_mul_f32_e32 v148, v156, v148
	v_mul_f32_e32 v150, v156, v150
	v_mul_f32_e32 v152, v156, v152
	v_mul_f32_e32 v154, v156, v154
	v_mul_f32_e32 v149, v156, v149
	v_mul_f32_e32 v151, v156, v151
	v_mul_f32_e32 v153, v156, v153
	v_mul_f32_e32 v155, v156, v155
	v_mul_f32_e32 v148, v148, v64
	v_mul_f32_e32 v149, v149, v65
	v_mul_f32_e32 v150, v150, v66
	v_mul_f32_e32 v151, v151, v67
	v_mul_f32_e32 v152, v152, v68
	v_mul_f32_e32 v153, v153, v69
	v_mul_f32_e32 v154, v154, v70
	v_mul_f32_e32 v155, v155, v71
	v_cvt_pk_bf16_f32 v12, v148, v149
	v_cvt_pk_bf16_f32 v13, v150, v151
	v_cvt_pk_bf16_f32 v14, v152, v153
	v_cvt_pk_bf16_f32 v15, v154, v155
	s_nop 0
	global_store_dwordx4 v[158:159], v[12:15], off offset:1536
	s_mov_b64 exec, s[10:11]
	s_and_saveexec_b64 s[10:11], s[42:43]
	v_fmamk_f32 v168, v168, 0x3b800000, v192
	v_rsq_f32_e32 v168, v168
	v_add_co_u32_e32 v170, vcc, 0x5006000, v28
	s_nop 1
	v_addc_co_u32_e32 v171, vcc, 0, v29, vcc
	v_mul_f32_e32 v160, v168, v160
	v_mul_f32_e32 v162, v168, v162
	v_mul_f32_e32 v164, v168, v164
	v_mul_f32_e32 v166, v168, v166
	v_mul_f32_e32 v161, v168, v161
	v_mul_f32_e32 v163, v168, v163
	v_mul_f32_e32 v165, v168, v165
	v_mul_f32_e32 v167, v168, v167
	v_mul_f32_e32 v160, v160, v72
	v_mul_f32_e32 v161, v161, v73
	v_mul_f32_e32 v162, v162, v74
	v_mul_f32_e32 v163, v163, v75
	v_mul_f32_e32 v164, v164, v76
	v_mul_f32_e32 v165, v165, v77
	v_mul_f32_e32 v166, v166, v78
	v_mul_f32_e32 v167, v167, v79
	v_cvt_pk_bf16_f32 v0, v160, v161
	v_cvt_pk_bf16_f32 v1, v162, v163
	v_cvt_pk_bf16_f32 v2, v164, v165
	v_cvt_pk_bf16_f32 v3, v166, v167
	s_nop 0
	global_store_dwordx4 v[170:171], v[0:3], off offset:2304
	s_mov_b64 exec, s[10:11]
	s_and_saveexec_b64 s[10:11], s[44:45]
	v_mul_f32_e32 v176, v33, v35
	v_fma_f32 v176, v7, v34, -v176
	v_mul_f32_e32 v177, v7, v35
	v_add_co_u32_e32 v178, vcc, 0x5006000, v30
	v_fmac_f32_e32 v177, v33, v34
	v_cvt_pk_bf16_f32 v176, v176, v177
	s_nop 0
	v_addc_co_u32_e32 v179, vcc, 0, v31, vcc
	global_store_short v[178:179], v176, off offset:2816
	global_store_short_d16_hi v[178:179], v176, off offset:2848
	s_mov_b64 exec, s[10:11]
	s_branch .LBB0_1526
